# attention row max / row sum: xor-32 step through v_permlane32_swap instead of ds_bpermute
# baseline (speedup 1.0000x reference)
.LBB0_1163:
	s_or_b64 exec, exec, s[16:17]
	v_lshlrev_b32_e32 v207, 7, v0
	v_mov_b32_e32 v0, s74
	v_cndmask_b32_e64 v0, v92, v0, s[38:39]
	v_cndmask_b32_e64 v0, v0, v92, s[36:37]
	v_max3_f32 v92, v99, s74, v98
	v_max3_f32 v92, v92, v2, v1
	v_max3_f32 v92, v92, v124, v125
	v_max3_f32 v92, v92, v126, v127
	v_max3_f32 v92, v92, v116, v117
	v_max3_f32 v92, v92, v118, v119
	v_max3_f32 v92, v92, v108, v109
	v_max3_f32 v92, v92, v110, v111
	v_max3_f32 v92, v92, v104, v105
	v_max3_f32 v92, v92, v106, v107
	v_max3_f32 v92, v92, v100, v101
	v_max3_f32 v92, v92, v102, v103
	v_max3_f32 v92, v92, v112, v113
	v_max3_f32 v92, v92, v114, v115
	v_and_b32_e32 v205, 64, v175
	v_max3_f32 v92, v92, v120, v121
	v_xor_b32_e32 v133, 16, v175
	v_add_u32_e32 v205, 64, v205
	v_cndmask_b32_e64 v93, v203, v93, s[36:37]
	v_max3_f32 v92, v92, v122, v123
	v_cmp_lt_i32_e32 vcc, v133, v205
	v_cndmask_b32_e64 v94, v94, v203, s[44:45]
	v_cndmask_b32_e64 v95, v95, v203, s[48:49]
	v_max3_f32 v92, v92, v0, v93
	v_cndmask_b32_e32 v133, v175, v133, vcc
	v_max3_f32 v92, v92, v94, v95
	v_lshlrev_b32_e32 v133, 2, v133
	ds_bpermute_b32 v209, v133, v92
	v_lshlrev_b32_e64 v96, v129, -1
	v_or_b32_e32 v97, v207, v155
	v_and_b32_e32 v208, 7, v135
	s_waitcnt lgkmcnt(0)
	v_max_f32_e32 v209, v209, v209
	v_max_f32_e32 v92, v92, v209
	v_xor_b32_e32 v209, 32, v175
	v_cmp_lt_i32_e32 vcc, v209, v205
	s_nop 1
	v_cndmask_b32_e32 v205, v175, v209, vcc
	v_lshlrev_b32_e32 v205, 2, v205
	v_mov_b32_e32 v209, v92
	s_nop 1
	v_permlane32_swap_b32_e32 v209, v92
	s_nop 0
	v_max_f32_e32 v209, v209, v209
	v_max_f32_e32 v92, v92, v209
	v_mul_f32_e32 v209, 0xbe38aa3b, v92
	v_fmamk_f32 v99, v99, 0x3e38aa3b, v209
	v_exp_f32_e32 v99, v99
	v_fmamk_f32 v98, v98, 0x3e38aa3b, v209
	v_exp_f32_e32 v98, v98
	v_fmamk_f32 v2, v2, 0x3e38aa3b, v209
	v_exp_f32_e32 v211, v2
	v_add_f32_e32 v210, 0, v99
	v_add_f32_e32 v210, v98, v210
	v_fmamk_f32 v1, v1, 0x3e38aa3b, v209
	v_add_f32_e32 v2, v211, v210
	v_exp_f32_e32 v210, v1
	v_cvt_pk_bf16_f32 v98, v99, v98
	v_fmamk_f32 v0, v0, 0x3e38aa3b, v209
	v_exp_f32_e32 v0, v0
	v_add_f32_e32 v1, v210, v2
	v_fmamk_f32 v2, v124, 0x3e38aa3b, v209
	v_exp_f32_e32 v124, v2
	v_fmamk_f32 v2, v125, 0x3e38aa3b, v209
	v_exp_f32_e32 v125, v2
	v_fmamk_f32 v2, v126, 0x3e38aa3b, v209
	v_exp_f32_e32 v126, v2
	v_fmamk_f32 v2, v127, 0x3e38aa3b, v209
	v_exp_f32_e32 v127, v2
	v_fmamk_f32 v2, v116, 0x3e38aa3b, v209
	v_exp_f32_e32 v212, v2
	v_fmamk_f32 v2, v117, 0x3e38aa3b, v209
	v_exp_f32_e32 v213, v2
	v_fmamk_f32 v2, v118, 0x3e38aa3b, v209
	v_exp_f32_e32 v118, v2
	v_fmamk_f32 v2, v119, 0x3e38aa3b, v209
	v_exp_f32_e32 v119, v2
	v_fmamk_f32 v2, v108, 0x3e38aa3b, v209
	v_exp_f32_e32 v214, v2
	v_fmamk_f32 v2, v109, 0x3e38aa3b, v209
	v_exp_f32_e32 v215, v2
	v_fmamk_f32 v2, v110, 0x3e38aa3b, v209
	v_exp_f32_e32 v216, v2
	v_fmamk_f32 v2, v111, 0x3e38aa3b, v209
	v_exp_f32_e32 v217, v2
	v_fmamk_f32 v2, v104, 0x3e38aa3b, v209
	v_exp_f32_e32 v218, v2
	v_fmamk_f32 v2, v105, 0x3e38aa3b, v209
	v_exp_f32_e32 v219, v2
	v_fmamk_f32 v2, v106, 0x3e38aa3b, v209
	v_exp_f32_e32 v220, v2
	v_fmamk_f32 v2, v107, 0x3e38aa3b, v209
	v_exp_f32_e32 v221, v2
	v_fmamk_f32 v2, v100, 0x3e38aa3b, v209
	v_exp_f32_e32 v222, v2
	v_fmamk_f32 v2, v101, 0x3e38aa3b, v209
	v_exp_f32_e32 v223, v2
	v_fmamk_f32 v2, v102, 0x3e38aa3b, v209
	v_exp_f32_e32 v224, v2
	v_fmamk_f32 v2, v103, 0x3e38aa3b, v209
	v_exp_f32_e32 v225, v2
	v_fmamk_f32 v2, v112, 0x3e38aa3b, v209
	v_add_f32_e32 v1, v124, v1
	v_exp_f32_e32 v226, v2
	v_fmamk_f32 v2, v113, 0x3e38aa3b, v209
	v_add_f32_e32 v1, v125, v1
	v_exp_f32_e32 v227, v2
	v_fmamk_f32 v2, v114, 0x3e38aa3b, v209
	v_add_f32_e32 v1, v126, v1
	v_exp_f32_e32 v228, v2
	v_fmamk_f32 v2, v115, 0x3e38aa3b, v209
	ds_read_b64_tr_b16 v[104:105], v177 offset:36864
	ds_read_b64_tr_b16 v[108:109], v177 offset:36896
	ds_read_b64_tr_b16 v[102:103], v176 offset:36864
	ds_read_b64_tr_b16 v[106:107], v176 offset:36896
	ds_read_b64_tr_b16 v[110:111], v176 offset:36928
	ds_read_b64_tr_b16 v[112:113], v177 offset:36928
	ds_read_b64_tr_b16 v[114:115], v176 offset:36960
	ds_read_b64_tr_b16 v[116:117], v177 offset:36960
	v_add_f32_e32 v1, v127, v1
	v_add_f32_e32 v1, v212, v1
	v_exp_f32_e32 v229, v2
	v_fmamk_f32 v2, v120, 0x3e38aa3b, v209
	v_add_f32_e32 v1, v213, v1
	v_exp_f32_e32 v230, v2
	v_fmamk_f32 v2, v121, 0x3e38aa3b, v209
	v_add_f32_e32 v1, v118, v1
	v_exp_f32_e32 v231, v2
	v_fmamk_f32 v2, v122, 0x3e38aa3b, v209
	v_cvt_pk_bf16_f32 v99, v211, v210
	v_cvt_pk_bf16_f32 v100, v124, v125
	v_cvt_pk_bf16_f32 v101, v126, v127
	v_add_f32_e32 v1, v119, v1
	v_exp_f32_e32 v232, v2
	v_fmamk_f32 v2, v123, 0x3e38aa3b, v209
	s_waitcnt lgkmcnt(5)
	v_mfma_f32_16x16x32_bf16 v[102:105], v[102:105], v[98:101], 0
	v_add_f32_e32 v1, v214, v1
	v_add_f32_e32 v1, v215, v1
	v_add_f32_e32 v1, v216, v1
	s_waitcnt lgkmcnt(4)
	v_mfma_f32_16x16x32_bf16 v[106:109], v[106:109], v[98:101], 0
	v_add_f32_e32 v1, v217, v1
	v_exp_f32_e32 v233, v2
	v_add_f32_e32 v1, v218, v1
	s_waitcnt lgkmcnt(2)
	v_mfma_f32_16x16x32_bf16 v[110:113], v[110:113], v[98:101], 0
	v_add_f32_e32 v1, v219, v1
	v_add_f32_e32 v1, v220, v1
	v_add_f32_e32 v1, v221, v1
	s_waitcnt lgkmcnt(0)
	v_mfma_f32_16x16x32_bf16 v[98:101], v[114:117], v[98:101], 0
	v_cvt_pk_bf16_f32 v115, v118, v119
	ds_read_b64_tr_b16 v[120:121], v179 offset:36864
	ds_read_b64_tr_b16 v[124:125], v179 offset:36896
	ds_read_b64_tr_b16 v[118:119], v178 offset:36864
	ds_read_b64_tr_b16 v[122:123], v178 offset:36896
	v_cvt_pk_bf16_f32 v114, v212, v213
	v_cvt_pk_bf16_f32 v116, v214, v215
	v_cvt_pk_bf16_f32 v117, v216, v217
	v_add_f32_e32 v1, v222, v1
	v_add_f32_e32 v1, v223, v1
	s_waitcnt lgkmcnt(1)
	v_mfma_f32_16x16x32_bf16 v[102:105], v[118:121], v[114:117], v[102:105]
	ds_read_b64_tr_b16 v[118:119], v178 offset:36928
	ds_read_b64_tr_b16 v[120:121], v179 offset:36928
	v_add_f32_e32 v1, v224, v1
	v_add_f32_e32 v1, v225, v1
	s_waitcnt lgkmcnt(0)
	v_mfma_f32_16x16x32_bf16 v[110:113], v[118:121], v[114:117], v[110:113]
	ds_read_b64_tr_b16 v[118:119], v178 offset:36960
	ds_read_b64_tr_b16 v[120:121], v179 offset:36960
	v_add_f32_e32 v1, v226, v1
	v_add_f32_e32 v1, v227, v1
	v_mfma_f32_16x16x32_bf16 v[106:109], v[122:125], v[114:117], v[106:109]
	v_add_f32_e32 v1, v228, v1
	v_add_f32_e32 v1, v229, v1
	v_add_f32_e32 v1, v230, v1
	s_waitcnt lgkmcnt(0)
	v_mfma_f32_16x16x32_bf16 v[98:101], v[118:121], v[114:117], v[98:101]
	ds_read_b64_tr_b16 v[120:121], v181 offset:36864
	ds_read_b64_tr_b16 v[124:125], v181 offset:36896
	ds_read_b64_tr_b16 v[118:119], v180 offset:36864
	ds_read_b64_tr_b16 v[122:123], v180 offset:36896
	v_cvt_pk_bf16_f32 v114, v218, v219
	v_cvt_pk_bf16_f32 v115, v220, v221
	v_cvt_pk_bf16_f32 v116, v222, v223
	v_cvt_pk_bf16_f32 v117, v224, v225
	v_fmamk_f32 v2, v93, 0x3e38aa3b, v209
	v_add_f32_e32 v1, v231, v1
	s_waitcnt lgkmcnt(1)
	v_mfma_f32_16x16x32_bf16 v[102:105], v[118:121], v[114:117], v[102:105]
	ds_read_b64_tr_b16 v[118:119], v180 offset:36928
	ds_read_b64_tr_b16 v[120:121], v181 offset:36928
	v_exp_f32_e32 v2, v2
	v_add_f32_e32 v1, v232, v1
	s_waitcnt lgkmcnt(0)
	v_mfma_f32_16x16x32_bf16 v[110:113], v[118:121], v[114:117], v[110:113]
	ds_read_b64_tr_b16 v[118:119], v180 offset:36960
	ds_read_b64_tr_b16 v[120:121], v181 offset:36960
	v_add_f32_e32 v1, v233, v1
	v_add_f32_e32 v1, v0, v1
	v_mfma_f32_16x16x32_bf16 v[106:109], v[122:125], v[114:117], v[106:109]
	v_add_f32_e32 v93, v2, v1
	v_fmamk_f32 v1, v94, 0x3e38aa3b, v209
	v_fmac_f32_e32 v209, 0x3e38aa3b, v95
	s_waitcnt lgkmcnt(0)
	v_mfma_f32_16x16x32_bf16 v[98:101], v[118:121], v[114:117], v[98:101]
	ds_read_b64_tr_b16 v[120:121], v183 offset:36864
	ds_read_b64_tr_b16 v[124:125], v183 offset:36896
	ds_read_b64_tr_b16 v[118:119], v182 offset:36864
	ds_read_b64_tr_b16 v[122:123], v182 offset:36896
	v_cvt_pk_bf16_f32 v114, v226, v227
	v_cvt_pk_bf16_f32 v115, v228, v229
	v_cvt_pk_bf16_f32 v116, v230, v231
	v_cvt_pk_bf16_f32 v117, v232, v233
	v_exp_f32_e32 v1, v1
	v_exp_f32_e32 v95, v209
	s_waitcnt lgkmcnt(1)
	v_mfma_f32_16x16x32_bf16 v[102:105], v[118:121], v[114:117], v[102:105]
	ds_read_b64_tr_b16 v[118:119], v182 offset:36928
	ds_read_b64_tr_b16 v[120:121], v183 offset:36928
	v_add_f32_e32 v93, v1, v93
	v_cvt_pk_bf16_f32 v1, v1, v95
	s_waitcnt lgkmcnt(0)
	v_mfma_f32_16x16x32_bf16 v[110:113], v[118:121], v[114:117], v[110:113]
	ds_read_b64_tr_b16 v[118:119], v182 offset:36960
	ds_read_b64_tr_b16 v[120:121], v183 offset:36960
	v_cvt_pk_bf16_f32 v0, v0, v2
	v_mov_b32_e32 v2, v3
	v_mfma_f32_16x16x32_bf16 v[106:109], v[122:125], v[114:117], v[106:109]
	v_add_f32_e32 v93, v95, v93
	ds_bpermute_b32 v94, v133, v93
	s_waitcnt lgkmcnt(0)
	v_add_f32_e32 v93, v93, v94
	v_mfma_f32_16x16x32_bf16 v[98:101], v[118:121], v[114:117], v[98:101]
	ds_read_b64_tr_b16 v[114:115], v184 offset:36864
	ds_read_b64_tr_b16 v[118:119], v184 offset:36896
	s_waitcnt lgkmcnt(1)
	v_mov_b32_e32 v116, v114
	v_mov_b32_e32 v117, v115
	s_waitcnt lgkmcnt(0)
	v_mov_b32_e32 v120, v118
	v_mov_b32_e32 v121, v119
	v_mfma_f32_16x16x32_bf16 v[102:105], v[114:117], v[0:3], v[102:105]
	ds_read_b64_tr_b16 v[114:115], v184 offset:36928
	v_mov_b32_e32 v94, v93
	s_nop 1
	v_permlane32_swap_b32_e32 v94, v93
	s_nop 0
	v_add_f32_e32 v93, v93, v94
	s_waitcnt lgkmcnt(0)
	v_mov_b32_e32 v116, v114
	v_mov_b32_e32 v117, v115
	v_mfma_f32_16x16x32_bf16 v[106:109], v[118:121], v[0:3], v[106:109]
	s_nop 0
	v_mfma_f32_16x16x32_bf16 v[110:113], v[114:117], v[0:3], v[110:113]
	ds_read_b64_tr_b16 v[114:115], v184 offset:36960
	s_waitcnt lgkmcnt(0)
	v_mov_b32_e32 v116, v114
	v_mov_b32_e32 v117, v115
	s_nop 1
	v_mfma_f32_16x16x32_bf16 v[98:101], v[114:117], v[0:3], v[98:101]
	v_div_scale_f32 v0, s[16:17], v93, v93, 1.0
	v_rcp_f32_e32 v1, v0
	s_nop 0
	v_fma_f32 v2, -v0, v1, 1.0
	v_fmac_f32_e32 v1, v2, v1
	v_div_scale_f32 v2, vcc, 1.0, v93, 1.0
	v_mul_f32_e32 v94, v2, v1
	v_fma_f32 v95, -v0, v94, v2
	v_fmac_f32_e32 v94, v95, v1
	v_fma_f32 v0, -v0, v94, v2
	v_div_fmas_f32 v0, v0, v1, v94
	v_div_fixup_f32 v94, v0, v93, 1.0
	v_lshlrev_b32_e32 v0, 9, v135
	v_and_b32_e32 v0, 0x7ffff000, v0
	v_bitop3_b32 v122, v206, v0, v96 bitop3:0xdc
	v_lshl_add_u32 v2, v97, v129, v122
	v_mov_b64_e32 v[0:1], s[78:79]
	v_mad_u64_u32 v[0:1], s[16:17], v2, s26, v[0:1]
	v_lshlrev_b32_e32 v2, 10, v131
	v_lshl_add_u64 v[96:97], v[0:1], 0, v[2:3]
	v_lshlrev_b32_e32 v2, 7, v208
	v_lshl_add_u64 v[96:97], v[96:97], 0, v[2:3]
	v_mov_b32_e32 v135, v3
	v_pk_mul_f32 v[102:103], v[102:103], v[94:95] op_sel_hi:[1,0]
	v_pk_mul_f32 v[104:105], v[104:105], v[94:95] op_sel_hi:[1,0]
	v_lshl_add_u64 v[96:97], v[96:97], 0, v[134:135]
	v_cvt_pk_bf16_f32 v102, v102, v103
	v_cvt_pk_bf16_f32 v103, v104, v105
	global_store_dwordx2 v[96:97], v[102:103], off
	v_pk_mul_f32 v[102:103], v[106:107], v[94:95] op_sel_hi:[1,0]
	v_pk_mul_f32 v[104:105], v[108:109], v[94:95] op_sel_hi:[1,0]
	v_cvt_pk_bf16_f32 v102, v102, v103
	v_cvt_pk_bf16_f32 v103, v104, v105
	global_store_dwordx2 v[96:97], v[102:103], off offset:32
	v_pk_mul_f32 v[102:103], v[110:111], v[94:95] op_sel_hi:[1,0]
	v_pk_mul_f32 v[104:105], v[112:113], v[94:95] op_sel_hi:[1,0]
	v_pk_mul_f32 v[98:99], v[98:99], v[94:95] op_sel_hi:[1,0]
	v_pk_mul_f32 v[94:95], v[100:101], v[94:95] op_sel_hi:[1,0]
	v_lshlrev_b32_e32 v2, 2, v208
	v_cvt_pk_bf16_f32 v102, v102, v103
	v_cvt_pk_bf16_f32 v103, v104, v105
	v_cvt_pk_bf16_f32 v98, v98, v99
	v_cvt_pk_bf16_f32 v99, v94, v95
	v_lshl_or_b32 v120, v131, 5, v2
	global_store_dwordx2 v[96:97], v[102:103], off offset:64
	global_store_dwordx2 v[96:97], v[98:99], off offset:96
	s_and_saveexec_b64 s[16:17], s[60:61]
	s_cbranch_execz .LBB0_1165
	v_cmp_gt_f32_e32 vcc, s75, v93
	v_mov_b32_e32 v121, v3
	v_lshl_add_u64 v[0:1], v[0:1], 0, v[120:121]
	v_cndmask_b32_e64 v2, 0, 32, vcc
	v_ldexp_f32 v2, v93, v2
	v_log_f32_e32 v2, v2
	s_nop 0
	v_mul_f32_e32 v93, 0x3f317217, v2
	v_fma_f32 v93, v2, s82, -v93
	v_fmac_f32_e32 v93, 0x3377d1cf, v2
	v_fmac_f32_e32 v93, 0x3f317217, v2
	v_cmp_lt_f32_e64 s[70:71], |v2|, s83
	s_nop 1
	v_cndmask_b32_e64 v2, v2, v93, s[70:71]
	v_cndmask_b32_e32 v93, 0, v204, vcc
	v_sub_f32_e32 v2, v2, v93
	v_fmac_f32_e32 v2, 0x3e000000, v92
	global_store_dword v[0:1], v2, off offset:3072

.LBB0_1167:
	s_or_b64 exec, exec, s[16:17]
	v_mov_b32_e32 v124, s74
	v_cndmask_b32_e64 v121, v84, v124, s[38:39]
	v_cndmask_b32_e64 v121, v121, v84, s[36:37]
	v_max3_f32 v84, v2, s74, v91
	v_max3_f32 v84, v84, v1, v0
	v_max3_f32 v84, v84, v116, v117
	v_max3_f32 v84, v84, v118, v119
	v_max3_f32 v84, v84, v112, v113
	v_max3_f32 v84, v84, v114, v115
	v_max3_f32 v84, v84, v108, v109
	v_max3_f32 v84, v84, v110, v111
	v_max3_f32 v84, v84, v104, v105
	v_max3_f32 v84, v84, v106, v107
	v_max3_f32 v84, v84, v100, v101
	v_max3_f32 v84, v84, v102, v103
	v_max3_f32 v84, v84, v92, v93
	v_max3_f32 v84, v84, v94, v95
	v_max3_f32 v84, v84, v96, v97
	v_cndmask_b32_e64 v85, v203, v85, s[36:37]
	v_max3_f32 v84, v84, v98, v99
	v_cndmask_b32_e64 v86, v86, v203, s[44:45]
	v_cndmask_b32_e64 v87, v87, v203, s[48:49]
	v_max3_f32 v84, v84, v121, v85
	v_max3_f32 v84, v84, v86, v87
	ds_bpermute_b32 v123, v133, v84
	v_lshlrev_b32_e32 v89, 9, v131
	v_or_b32_e32 v90, v207, v137
	v_lshlrev_b32_e32 v88, 6, v208
	s_waitcnt lgkmcnt(0)
	v_max_f32_e32 v123, v123, v123
	v_max_f32_e32 v84, v84, v123
	v_mov_b32_e32 v123, v84
	s_nop 1
	v_permlane32_swap_b32_e32 v123, v84
	s_nop 0
	v_max_f32_e32 v123, v123, v123
	v_max_f32_e32 v84, v84, v123
	v_mul_f32_e32 v123, 0xbe38aa3b, v84
	v_fmamk_f32 v2, v2, 0x3e38aa3b, v123
	v_exp_f32_e32 v2, v2
	v_fmamk_f32 v91, v91, 0x3e38aa3b, v123
	v_exp_f32_e32 v91, v91
	v_fmamk_f32 v1, v1, 0x3e38aa3b, v123
	v_exp_f32_e32 v1, v1
	v_fmamk_f32 v0, v0, 0x3e38aa3b, v123
	v_exp_f32_e32 v0, v0
	v_fmamk_f32 v116, v116, 0x3e38aa3b, v123
	v_add_f32_e32 v124, 0, v2
	v_exp_f32_e32 v116, v116
	v_fmamk_f32 v117, v117, 0x3e38aa3b, v123
	v_add_f32_e32 v124, v91, v124
	v_exp_f32_e32 v117, v117
	v_fmamk_f32 v118, v118, 0x3e38aa3b, v123
	v_add_f32_e32 v124, v1, v124
	v_exp_f32_e32 v118, v118
	v_fmamk_f32 v119, v119, 0x3e38aa3b, v123
	v_add_f32_e32 v124, v0, v124
	v_exp_f32_e32 v119, v119
	v_fmamk_f32 v112, v112, 0x3e38aa3b, v123
	v_add_f32_e32 v124, v116, v124
	v_exp_f32_e32 v112, v112
	v_fmamk_f32 v113, v113, 0x3e38aa3b, v123
	v_add_f32_e32 v124, v117, v124
	v_exp_f32_e32 v113, v113
	v_fmamk_f32 v114, v114, 0x3e38aa3b, v123
	v_add_f32_e32 v124, v118, v124
	v_exp_f32_e32 v114, v114
	v_fmamk_f32 v115, v115, 0x3e38aa3b, v123
	v_add_f32_e32 v124, v119, v124
	v_exp_f32_e32 v115, v115
	v_fmamk_f32 v108, v108, 0x3e38aa3b, v123
	v_add_f32_e32 v124, v112, v124
	v_exp_f32_e32 v125, v108
	v_add_f32_e32 v124, v113, v124
	v_add_f32_e32 v124, v114, v124
	v_add_f32_e32 v124, v115, v124
	v_fmamk_f32 v109, v109, 0x3e38aa3b, v123
	v_add_f32_e32 v108, v125, v124
	v_exp_f32_e32 v124, v109
	v_fmamk_f32 v109, v110, 0x3e38aa3b, v123
	v_exp_f32_e32 v126, v109
	v_fmamk_f32 v109, v111, 0x3e38aa3b, v123
	v_exp_f32_e32 v127, v109
	v_fmamk_f32 v104, v104, 0x3e38aa3b, v123
	v_exp_f32_e32 v131, v104
	v_fmamk_f32 v105, v105, 0x3e38aa3b, v123
	v_add_f32_e32 v108, v124, v108
	v_exp_f32_e32 v135, v105
	v_fmamk_f32 v105, v106, 0x3e38aa3b, v123
	v_add_f32_e32 v108, v126, v108
	v_exp_f32_e32 v206, v105
	v_fmamk_f32 v105, v107, 0x3e38aa3b, v123
	v_add_f32_e32 v108, v127, v108
	v_exp_f32_e32 v207, v105
	v_fmamk_f32 v100, v100, 0x3e38aa3b, v123
	v_add_f32_e32 v104, v131, v108
	v_exp_f32_e32 v208, v100
	v_fmamk_f32 v101, v101, 0x3e38aa3b, v123
	v_add_f32_e32 v104, v135, v104
	v_exp_f32_e32 v209, v101
	v_fmamk_f32 v101, v102, 0x3e38aa3b, v123
	v_add_f32_e32 v104, v206, v104
	v_exp_f32_e32 v210, v101
	v_fmamk_f32 v101, v103, 0x3e38aa3b, v123
	v_add_f32_e32 v104, v207, v104
	v_exp_f32_e32 v211, v101
	v_fmamk_f32 v92, v92, 0x3e38aa3b, v123
	v_add_f32_e32 v100, v208, v104
	v_exp_f32_e32 v212, v92
	v_fmamk_f32 v93, v93, 0x3e38aa3b, v123
	v_add_f32_e32 v100, v209, v100
	v_exp_f32_e32 v213, v93
	v_fmamk_f32 v93, v94, 0x3e38aa3b, v123
	v_add_f32_e32 v100, v210, v100
	v_exp_f32_e32 v214, v93
	v_fmamk_f32 v93, v95, 0x3e38aa3b, v123
	v_add_f32_e32 v100, v211, v100
	v_exp_f32_e32 v215, v93
	v_fmamk_f32 v93, v96, 0x3e38aa3b, v123
	v_add_f32_e32 v92, v212, v100
	v_exp_f32_e32 v216, v93
	v_fmamk_f32 v93, v97, 0x3e38aa3b, v123
	v_add_f32_e32 v92, v213, v92
	v_exp_f32_e32 v217, v93
	v_fmamk_f32 v93, v98, 0x3e38aa3b, v123
	v_add_f32_e32 v92, v214, v92
	v_exp_f32_e32 v218, v93
	v_fmamk_f32 v93, v99, 0x3e38aa3b, v123
	v_add_f32_e32 v92, v215, v92
	v_exp_f32_e32 v219, v93
	v_fmamk_f32 v93, v121, 0x3e38aa3b, v123
	v_add_f32_e32 v92, v216, v92
	v_exp_f32_e32 v121, v93
	v_fmamk_f32 v85, v85, 0x3e38aa3b, v123
	v_add_f32_e32 v92, v217, v92
	v_exp_f32_e32 v220, v85
	ds_read_b64_tr_b16 v[98:99], v195 offset:36864
	ds_read_b64_tr_b16 v[102:103], v195 offset:36896
	ds_read_b64_tr_b16 v[96:97], v194 offset:36864
	ds_read_b64_tr_b16 v[100:101], v194 offset:36896
	ds_read_b64_tr_b16 v[104:105], v194 offset:36928
	ds_read_b64_tr_b16 v[106:107], v195 offset:36928
	ds_read_b64_tr_b16 v[108:109], v194 offset:36960
	ds_read_b64_tr_b16 v[110:111], v195 offset:36960
	v_add_f32_e32 v92, v218, v92
	v_add_f32_e32 v92, v219, v92
	v_add_f32_e32 v92, v121, v92
	v_add_f32_e32 v85, v220, v92
	v_cvt_pk_bf16_f32 v92, v2, v91
	v_cvt_pk_bf16_f32 v93, v1, v0
	v_cvt_pk_bf16_f32 v94, v116, v117
	v_cvt_pk_bf16_f32 v95, v118, v119
	v_fmamk_f32 v86, v86, 0x3e38aa3b, v123
	v_fmac_f32_e32 v123, 0x3e38aa3b, v87
	s_waitcnt lgkmcnt(5)
	v_mfma_f32_16x16x32_bf16 v[96:99], v[96:99], v[92:95], 0
	v_exp_f32_e32 v221, v86
	v_exp_f32_e32 v87, v123
	v_cvt_pk_bf16_f32 v0, v121, v220
	s_waitcnt lgkmcnt(4)
	v_mfma_f32_16x16x32_bf16 v[100:103], v[100:103], v[92:95], 0
	v_mov_b32_e32 v2, v3
	v_cvt_pk_bf16_f32 v1, v221, v87
	v_add_f32_e32 v85, v221, v85
	s_waitcnt lgkmcnt(2)
	v_mfma_f32_16x16x32_bf16 v[104:107], v[104:107], v[92:95], 0
	v_add_f32_e32 v85, v87, v85
	ds_bpermute_b32 v86, v133, v85
	s_waitcnt lgkmcnt(0)
	v_add_f32_e32 v85, v85, v86
	v_mfma_f32_16x16x32_bf16 v[92:95], v[108:111], v[92:95], 0
	v_cvt_pk_bf16_f32 v108, v112, v113
	v_cvt_pk_bf16_f32 v109, v114, v115
	ds_read_b64_tr_b16 v[114:115], v197 offset:36864
	ds_read_b64_tr_b16 v[118:119], v197 offset:36896
	ds_read_b64_tr_b16 v[112:113], v196 offset:36864
	ds_read_b64_tr_b16 v[116:117], v196 offset:36896
	v_cvt_pk_bf16_f32 v110, v125, v124
	v_cvt_pk_bf16_f32 v111, v126, v127
	v_mov_b32_e32 v86, v85
	s_nop 1
	v_permlane32_swap_b32_e32 v86, v85
	s_nop 0
	s_waitcnt lgkmcnt(0)
	v_add_f32_e32 v85, v85, v86
	v_mfma_f32_16x16x32_bf16 v[96:99], v[112:115], v[108:111], v[96:99]
	ds_read_b64_tr_b16 v[112:113], v196 offset:36928
	ds_read_b64_tr_b16 v[114:115], v197 offset:36928
	s_waitcnt lgkmcnt(0)
	v_mfma_f32_16x16x32_bf16 v[104:107], v[112:115], v[108:111], v[104:107]
	ds_read_b64_tr_b16 v[112:113], v196 offset:36960
	ds_read_b64_tr_b16 v[114:115], v197 offset:36960
	v_mfma_f32_16x16x32_bf16 v[100:103], v[116:119], v[108:111], v[100:103]
	s_waitcnt lgkmcnt(0)
	v_mfma_f32_16x16x32_bf16 v[92:95], v[112:115], v[108:111], v[92:95]
	ds_read_b64_tr_b16 v[114:115], v199 offset:36864
	ds_read_b64_tr_b16 v[118:119], v199 offset:36896
	ds_read_b64_tr_b16 v[112:113], v198 offset:36864
	ds_read_b64_tr_b16 v[116:117], v198 offset:36896
	v_cvt_pk_bf16_f32 v108, v131, v135
	v_cvt_pk_bf16_f32 v109, v206, v207
	v_cvt_pk_bf16_f32 v110, v208, v209
	v_cvt_pk_bf16_f32 v111, v210, v211
	v_mov_b32_e32 v135, v3
	s_waitcnt lgkmcnt(1)
	v_mfma_f32_16x16x32_bf16 v[96:99], v[112:115], v[108:111], v[96:99]
	ds_read_b64_tr_b16 v[112:113], v198 offset:36928
	ds_read_b64_tr_b16 v[114:115], v199 offset:36928
	s_waitcnt lgkmcnt(0)
	v_mfma_f32_16x16x32_bf16 v[104:107], v[112:115], v[108:111], v[104:107]
	ds_read_b64_tr_b16 v[112:113], v198 offset:36960
	ds_read_b64_tr_b16 v[114:115], v199 offset:36960
	v_mfma_f32_16x16x32_bf16 v[100:103], v[116:119], v[108:111], v[100:103]
	s_waitcnt lgkmcnt(0)
	v_mfma_f32_16x16x32_bf16 v[92:95], v[112:115], v[108:111], v[92:95]
	ds_read_b64_tr_b16 v[114:115], v201 offset:36864
	ds_read_b64_tr_b16 v[118:119], v201 offset:36896
	ds_read_b64_tr_b16 v[112:113], v200 offset:36864
	ds_read_b64_tr_b16 v[116:117], v200 offset:36896
	v_cvt_pk_bf16_f32 v108, v212, v213
	v_cvt_pk_bf16_f32 v109, v214, v215
	v_cvt_pk_bf16_f32 v110, v216, v217
	v_cvt_pk_bf16_f32 v111, v218, v219
	s_waitcnt lgkmcnt(1)
	s_nop 0
	v_mfma_f32_16x16x32_bf16 v[96:99], v[112:115], v[108:111], v[96:99]
	ds_read_b64_tr_b16 v[112:113], v200 offset:36928
	ds_read_b64_tr_b16 v[114:115], v201 offset:36928
	s_waitcnt lgkmcnt(0)
	v_mfma_f32_16x16x32_bf16 v[104:107], v[112:115], v[108:111], v[104:107]
	ds_read_b64_tr_b16 v[112:113], v200 offset:36960
	ds_read_b64_tr_b16 v[114:115], v201 offset:36960
	v_mfma_f32_16x16x32_bf16 v[100:103], v[116:119], v[108:111], v[100:103]
	s_waitcnt lgkmcnt(0)
	v_mfma_f32_16x16x32_bf16 v[92:95], v[112:115], v[108:111], v[92:95]
	ds_read_b64_tr_b16 v[108:109], v202 offset:36864
	ds_read_b64_tr_b16 v[112:113], v202 offset:36896
	s_waitcnt lgkmcnt(1)
	v_mov_b32_e32 v110, v108
	v_mov_b32_e32 v111, v109
	s_waitcnt lgkmcnt(0)
	v_mov_b32_e32 v114, v112
	v_mov_b32_e32 v115, v113
	v_mfma_f32_16x16x32_bf16 v[96:99], v[108:111], v[0:3], v[96:99]
	ds_read_b64_tr_b16 v[108:109], v202 offset:36928
	s_waitcnt lgkmcnt(0)
	v_mov_b32_e32 v110, v108
	v_mov_b32_e32 v111, v109
	v_mfma_f32_16x16x32_bf16 v[100:103], v[112:115], v[0:3], v[100:103]
	s_nop 0
	v_mfma_f32_16x16x32_bf16 v[104:107], v[108:111], v[0:3], v[104:107]
	ds_read_b64_tr_b16 v[108:109], v202 offset:36960
	s_waitcnt lgkmcnt(0)
	v_mov_b32_e32 v110, v108
	v_mov_b32_e32 v111, v109
	s_nop 1
	v_mfma_f32_16x16x32_bf16 v[92:95], v[108:111], v[0:3], v[92:95]
	v_div_scale_f32 v0, s[16:17], v85, v85, 1.0
	v_rcp_f32_e32 v1, v0
	s_nop 0
	v_fma_f32 v2, -v0, v1, 1.0
	v_fmac_f32_e32 v1, v2, v1
	v_div_scale_f32 v2, vcc, 1.0, v85, 1.0
	v_mul_f32_e32 v86, v2, v1
	v_fma_f32 v87, -v0, v86, v2
	v_fmac_f32_e32 v86, v87, v1
	v_fma_f32 v0, -v0, v86, v2
	v_div_fmas_f32 v0, v0, v1, v86
	v_div_fixup_f32 v86, v0, v85, 1.0
	v_lshl_add_u32 v2, v90, v129, v122
	v_mov_b64_e32 v[0:1], s[78:79]
	v_mad_u64_u32 v[0:1], s[16:17], v2, s26, v[0:1]
	v_lshlrev_b32_e32 v2, 1, v89
	v_lshl_add_u64 v[90:91], v[0:1], 0, v[2:3]
	v_lshlrev_b32_e32 v2, 1, v88
	v_lshl_add_u64 v[88:89], v[90:91], 0, v[2:3]
	v_pk_mul_f32 v[90:91], v[96:97], v[86:87] op_sel_hi:[1,0]
	v_pk_mul_f32 v[96:97], v[98:99], v[86:87] op_sel_hi:[1,0]
	v_lshl_add_u64 v[88:89], v[88:89], 0, v[134:135]
	v_cvt_pk_bf16_f32 v90, v90, v91
	v_cvt_pk_bf16_f32 v91, v96, v97
	global_store_dwordx2 v[88:89], v[90:91], off
	v_pk_mul_f32 v[90:91], v[100:101], v[86:87] op_sel_hi:[1,0]
	v_pk_mul_f32 v[96:97], v[102:103], v[86:87] op_sel_hi:[1,0]
	v_cvt_pk_bf16_f32 v90, v90, v91
	v_cvt_pk_bf16_f32 v91, v96, v97
	global_store_dwordx2 v[88:89], v[90:91], off offset:32
	v_pk_mul_f32 v[90:91], v[104:105], v[86:87] op_sel_hi:[1,0]
	v_pk_mul_f32 v[96:97], v[106:107], v[86:87] op_sel_hi:[1,0]
	v_cvt_pk_bf16_f32 v90, v90, v91
	v_cvt_pk_bf16_f32 v91, v96, v97
	global_store_dwordx2 v[88:89], v[90:91], off offset:64
	v_pk_mul_f32 v[90:91], v[92:93], v[86:87] op_sel_hi:[1,0]
	v_pk_mul_f32 v[86:87], v[94:95], v[86:87] op_sel_hi:[1,0]
	v_cvt_pk_bf16_f32 v90, v90, v91
	v_cvt_pk_bf16_f32 v91, v86, v87
	global_store_dwordx2 v[88:89], v[90:91], off offset:96
	s_and_saveexec_b64 s[16:17], s[60:61]
	s_cbranch_execz .LBB0_1150
	v_cmp_gt_f32_e32 vcc, s75, v85
	v_mov_b32_e32 v121, v3
	v_lshl_add_u64 v[0:1], v[0:1], 0, v[120:121]
	v_cndmask_b32_e64 v2, 0, 32, vcc
	v_ldexp_f32 v2, v85, v2
	v_log_f32_e32 v2, v2
	s_nop 0
	v_mul_f32_e32 v85, 0x3f317217, v2
	v_fma_f32 v85, v2, s82, -v85
	v_fmac_f32_e32 v85, 0x3377d1cf, v2
	v_fmac_f32_e32 v85, 0x3f317217, v2
	v_cmp_lt_f32_e64 s[66:67], |v2|, s83
	s_nop 1
	v_cndmask_b32_e64 v2, v2, v85, s[66:67]
	v_cndmask_b32_e32 v85, 0, v204, vcc
	v_sub_f32_e32 v2, v2, v85
	v_fmac_f32_e32 v2, 0x3e000000, v84
	global_store_dword v[0:1], v2, off offset:3072
	s_branch .LBB0_1150
